# gate/up: SP1 load segment reduced to LDS reads and two LDS-DMA loads (LDS addresses precomputed, SGPR-base DMA addressing, tile-selection SALU hoisted into the previous MFMA shadow)
# baseline (speedup 1.0000x reference)
.LBB0_3115:
	s_ashr_i32 s13, s12, 31
	s_lshl_b64 s[14:15], s[12:13], 20
	s_add_u32 s14, s20, s14
	s_addc_u32 s15, s21, s15
	s_and_b64 s[18:19], s[2:3], exec
	s_cselect_b32 s13, s15, s35
	s_cselect_b32 s69, s14, s34
	s_ashr_i32 s11, s10, 31
	s_lshl_b64 s[18:19], s[10:11], 20
	s_add_u32 s24, s22, s18
	s_addc_u32 s25, s23, s19
	s_and_b64 s[18:19], s[2:3], exec
	s_cselect_b32 s11, s25, s39
	s_cselect_b32 s70, s24, s38
	s_add_u32 s34, s34, 0x80080
	s_addc_u32 s35, s35, 0
	s_add_u32 s71, s38, 0x100
	v_mov_b32_e32 v4, 0
	s_addc_u32 s73, s39, 0
	s_mov_b32 s74, -2
	v_mov_b32_e32 v5, v4
	v_mov_b32_e32 v6, v4
	v_mov_b32_e32 v7, v4
	v_mov_b32_e32 v12, v4
	v_mov_b32_e32 v13, v4
	v_mov_b32_e32 v14, v4
	v_mov_b32_e32 v15, v4
	v_mov_b32_e32 v20, v4
	v_mov_b32_e32 v21, v4
	v_mov_b32_e32 v22, v4
	v_mov_b32_e32 v23, v4
	v_mov_b32_e32 v28, v4
	v_mov_b32_e32 v29, v4
	v_mov_b32_e32 v30, v4
	v_mov_b32_e32 v31, v4
	v_mov_b32_e32 v36, v4
	v_mov_b32_e32 v37, v4
	v_mov_b32_e32 v38, v4
	v_mov_b32_e32 v39, v4
	v_mov_b32_e32 v44, v4
	v_mov_b32_e32 v45, v4
	v_mov_b32_e32 v46, v4
	v_mov_b32_e32 v47, v4
	v_mov_b32_e32 v52, v4
	v_mov_b32_e32 v53, v4
	v_mov_b32_e32 v54, v4
	v_mov_b32_e32 v55, v4
	v_mov_b32_e32 v60, v4
	v_mov_b32_e32 v61, v4
	v_mov_b32_e32 v62, v4
	v_mov_b32_e32 v63, v4
	v_mov_b32_e32 v8, v4
	v_mov_b32_e32 v9, v4
	v_mov_b32_e32 v10, v4
	v_mov_b32_e32 v11, v4
	v_mov_b32_e32 v16, v4
	v_mov_b32_e32 v17, v4
	v_mov_b32_e32 v18, v4
	v_mov_b32_e32 v19, v4
	v_mov_b32_e32 v24, v4
	v_mov_b32_e32 v25, v4
	v_mov_b32_e32 v26, v4
	v_mov_b32_e32 v27, v4
	v_mov_b32_e32 v32, v4
	v_mov_b32_e32 v33, v4
	v_mov_b32_e32 v34, v4
	v_mov_b32_e32 v35, v4
	v_mov_b32_e32 v40, v4
	v_mov_b32_e32 v41, v4
	v_mov_b32_e32 v42, v4
	v_mov_b32_e32 v43, v4
	v_mov_b32_e32 v48, v4
	v_mov_b32_e32 v49, v4
	v_mov_b32_e32 v50, v4
	v_mov_b32_e32 v51, v4
	v_mov_b32_e32 v56, v4
	v_mov_b32_e32 v57, v4
	v_mov_b32_e32 v58, v4
	v_mov_b32_e32 v59, v4
	v_mov_b32_e32 v64, v4
	v_mov_b32_e32 v65, v4
	v_mov_b32_e32 v66, v4
	v_mov_b32_e32 v67, v4
	v_mov_b32_e32 v68, v4
	v_mov_b32_e32 v69, v4
	v_mov_b32_e32 v70, v4
	v_mov_b32_e32 v71, v4
	v_mov_b32_e32 v76, v4
	v_mov_b32_e32 v77, v4
	v_mov_b32_e32 v78, v4
	v_mov_b32_e32 v79, v4
	v_mov_b32_e32 v84, v4
	v_mov_b32_e32 v85, v4
	v_mov_b32_e32 v86, v4
	v_mov_b32_e32 v87, v4
	v_mov_b32_e32 v92, v4
	v_mov_b32_e32 v93, v4
	v_mov_b32_e32 v94, v4
	v_mov_b32_e32 v95, v4
	v_mov_b32_e32 v100, v4
	v_mov_b32_e32 v101, v4
	v_mov_b32_e32 v102, v4
	v_mov_b32_e32 v103, v4
	v_mov_b32_e32 v108, v4
	v_mov_b32_e32 v109, v4
	v_mov_b32_e32 v110, v4
	v_mov_b32_e32 v111, v4
	v_mov_b32_e32 v116, v4
	v_mov_b32_e32 v117, v4
	v_mov_b32_e32 v118, v4
	v_mov_b32_e32 v119, v4
	v_mov_b32_e32 v124, v4
	v_mov_b32_e32 v125, v4
	v_mov_b32_e32 v126, v4
	v_mov_b32_e32 v127, v4
	v_mov_b32_e32 v72, v4
	v_mov_b32_e32 v73, v4
	v_mov_b32_e32 v74, v4
	v_mov_b32_e32 v75, v4
	v_mov_b32_e32 v80, v4
	v_mov_b32_e32 v81, v4
	v_mov_b32_e32 v82, v4
	v_mov_b32_e32 v83, v4
	v_mov_b32_e32 v88, v4
	v_mov_b32_e32 v89, v4
	v_mov_b32_e32 v90, v4
	v_mov_b32_e32 v91, v4
	v_mov_b32_e32 v96, v4
	v_mov_b32_e32 v97, v4
	v_mov_b32_e32 v98, v4
	v_mov_b32_e32 v99, v4
	v_mov_b32_e32 v104, v4
	v_mov_b32_e32 v105, v4
	v_mov_b32_e32 v106, v4
	v_mov_b32_e32 v107, v4
	v_mov_b32_e32 v112, v4
	v_mov_b32_e32 v113, v4
	v_mov_b32_e32 v114, v4
	v_mov_b32_e32 v115, v4
	v_mov_b32_e32 v120, v4
	v_mov_b32_e32 v121, v4
	v_mov_b32_e32 v122, v4
	v_mov_b32_e32 v123, v4
	v_mov_b32_e32 v128, v4
	v_mov_b32_e32 v129, v4
	v_mov_b32_e32 v130, v4
	v_mov_b32_e32 v131, v4
	v_add_u32_e32 v218, s26, v144
	v_add_u32_e32 v219, s40, v144
	v_add_u32_e32 v220, s49, v144
	v_add_u32_e32 v221, s56, v144
	s_add_u32 s18, s34, 0xfff80080
	s_addc_u32 s19, s35, -1
	s_cmp_eq_u32 s74, 28
	s_cselect_b32 s39, s13, s19
	s_cselect_b32 s38, s69, s18
	s_cselect_b32 s19, s11, s73
	s_cselect_b32 s18, s70, s71
.LBB0_3116:
	ds_read_b128 v[146:149], v218
	ds_read_b128 v[150:153], v218 offset:1024
	ds_read_b128 v[154:157], v218 offset:2048
	ds_read_b128 v[158:161], v218 offset:3072
	ds_read_b128 v[162:165], v219
	ds_read_b128 v[166:169], v219 offset:1024
	ds_read_b128 v[170:173], v219 offset:2048
	ds_read_b128 v[174:177], v219 offset:3072
	s_add_i32 m0, s43, 0xc000
	ds_read_b128 v[178:181], v145
	ds_read_b128 v[182:185], v145 offset:1024
	ds_read_b128 v[186:189], v145 offset:2048
	ds_read_b128 v[190:193], v145 offset:3072
	ds_read_b128 v[194:197], v145 offset:4096
	ds_read_b128 v[198:201], v145 offset:5120
	ds_read_b128 v[202:205], v145 offset:6144
	ds_read_b128 v[206:209], v145 offset:7168
	global_load_lds_dwordx4 v138, s[34:35]
	s_add_i32 m0, s43, 0xe000
	s_nop 0
	global_load_lds_dwordx4 v140, s[34:35]
	s_waitcnt vmcnt(8)
	s_waitcnt lgkmcnt(0)
	s_barrier
	s_setprio 1
	s_waitcnt lgkmcnt(0)
	v_mfma_f32_16x16x32_bf16 v[128:131], v[146:149], v[178:181], v[128:131]
	v_mfma_f32_16x16x32_bf16 v[128:131], v[150:153], v[182:185], v[128:131]
	v_mfma_f32_16x16x32_bf16 v[112:115], v[146:149], v[186:189], v[112:115]
	v_mfma_f32_16x16x32_bf16 v[112:115], v[150:153], v[190:193], v[112:115]
	v_mfma_f32_16x16x32_bf16 v[96:99], v[146:149], v[194:197], v[96:99]
	v_mfma_f32_16x16x32_bf16 v[96:99], v[150:153], v[198:201], v[96:99]
	v_mfma_f32_16x16x32_bf16 v[80:83], v[146:149], v[202:205], v[80:83]
	v_mfma_f32_16x16x32_bf16 v[80:83], v[150:153], v[206:209], v[80:83]
	v_mfma_f32_16x16x32_bf16 v[72:75], v[154:157], v[202:205], v[72:75]
	v_mfma_f32_16x16x32_bf16 v[72:75], v[158:161], v[206:209], v[72:75]
	v_mfma_f32_16x16x32_bf16 v[88:91], v[154:157], v[194:197], v[88:91]
	v_mfma_f32_16x16x32_bf16 v[88:91], v[158:161], v[198:201], v[88:91]
	v_mfma_f32_16x16x32_bf16 v[104:107], v[154:157], v[186:189], v[104:107]
	v_mfma_f32_16x16x32_bf16 v[104:107], v[158:161], v[190:193], v[104:107]
	v_mfma_f32_16x16x32_bf16 v[120:123], v[154:157], v[178:181], v[120:123]
	v_mfma_f32_16x16x32_bf16 v[120:123], v[158:161], v[182:185], v[120:123]
	s_setprio 0
	s_setprio 1
	v_mfma_f32_16x16x32_bf16 v[124:127], v[162:165], v[178:181], v[124:127]
	v_mfma_f32_16x16x32_bf16 v[124:127], v[166:169], v[182:185], v[124:127]
	v_mfma_f32_16x16x32_bf16 v[108:111], v[162:165], v[186:189], v[108:111]
	v_mfma_f32_16x16x32_bf16 v[108:111], v[166:169], v[190:193], v[108:111]
	v_mfma_f32_16x16x32_bf16 v[92:95], v[162:165], v[194:197], v[92:95]
	v_mfma_f32_16x16x32_bf16 v[92:95], v[166:169], v[198:201], v[92:95]
	v_mfma_f32_16x16x32_bf16 v[76:79], v[162:165], v[202:205], v[76:79]
	v_mfma_f32_16x16x32_bf16 v[76:79], v[166:169], v[206:209], v[76:79]
	v_mfma_f32_16x16x32_bf16 v[68:71], v[170:173], v[202:205], v[68:71]
	v_mfma_f32_16x16x32_bf16 v[68:71], v[174:177], v[206:209], v[68:71]
	v_mfma_f32_16x16x32_bf16 v[84:87], v[170:173], v[194:197], v[84:87]
	v_mfma_f32_16x16x32_bf16 v[84:87], v[174:177], v[198:201], v[84:87]
	v_mfma_f32_16x16x32_bf16 v[100:103], v[170:173], v[186:189], v[100:103]
	v_mfma_f32_16x16x32_bf16 v[100:103], v[174:177], v[190:193], v[100:103]
	v_mfma_f32_16x16x32_bf16 v[116:119], v[170:173], v[178:181], v[116:119]
	v_mfma_f32_16x16x32_bf16 v[116:119], v[174:177], v[182:185], v[116:119]
	s_setprio 0
	s_barrier
	s_mov_b32 m0, s27
	v_lshl_add_u64 v[142:143], s[18:19], 0, v[2:3]
	s_add_u32 s76, s18, 0x80000
	ds_read_b128 v[178:181], v145 offset:16384
	ds_read_b128 v[182:185], v145 offset:17408
	ds_read_b128 v[186:189], v145 offset:18432
	ds_read_b128 v[190:193], v145 offset:19456
	ds_read_b128 v[194:197], v145 offset:20480
	ds_read_b128 v[198:201], v145 offset:21504
	ds_read_b128 v[202:205], v145 offset:22528
	ds_read_b128 v[206:209], v145 offset:23552
	global_load_lds_dwordx4 v[142:143], off
	v_lshl_add_u64 v[210:211], s[18:19], 0, v[132:133]
	s_mov_b32 m0, s37
	s_addc_u32 s77, s19, 0
	global_load_lds_dwordx4 v[210:211], off
	v_lshl_add_u64 v[212:213], s[76:77], 0, v[2:3]
	s_mov_b32 m0, s41
	v_lshl_add_u64 v[214:215], s[38:39], 0, v[134:135]
	global_load_lds_dwordx4 v[212:213], off
	v_lshl_add_u64 v[212:213], s[76:77], 0, v[132:133]
	s_mov_b32 m0, s42
	s_nop 0
	global_load_lds_dwordx4 v[212:213], off
	v_lshl_add_u64 v[212:213], s[38:39], 0, v[136:137]
	s_mov_b32 m0, s43
	s_nop 0
	global_load_lds_dwordx4 v[212:213], off
	s_mov_b32 m0, s44
	s_nop 0
	global_load_lds_dwordx4 v[214:215], off
	s_waitcnt vmcnt(8)
	s_waitcnt lgkmcnt(0)
	s_barrier
	s_setprio 1
	s_waitcnt lgkmcnt(0)
	v_mfma_f32_16x16x32_bf16 v[64:67], v[146:149], v[178:181], v[64:67]
	v_mfma_f32_16x16x32_bf16 v[64:67], v[150:153], v[182:185], v[64:67]
	v_mfma_f32_16x16x32_bf16 v[48:51], v[146:149], v[186:189], v[48:51]
	v_mfma_f32_16x16x32_bf16 v[48:51], v[150:153], v[190:193], v[48:51]
	v_mfma_f32_16x16x32_bf16 v[32:35], v[146:149], v[194:197], v[32:35]
	v_mfma_f32_16x16x32_bf16 v[32:35], v[150:153], v[198:201], v[32:35]
	v_mfma_f32_16x16x32_bf16 v[16:19], v[146:149], v[202:205], v[16:19]
	v_mfma_f32_16x16x32_bf16 v[16:19], v[150:153], v[206:209], v[16:19]
	v_mfma_f32_16x16x32_bf16 v[8:11], v[154:157], v[202:205], v[8:11]
	v_mfma_f32_16x16x32_bf16 v[8:11], v[158:161], v[206:209], v[8:11]
	v_mfma_f32_16x16x32_bf16 v[24:27], v[154:157], v[194:197], v[24:27]
	v_mfma_f32_16x16x32_bf16 v[24:27], v[158:161], v[198:201], v[24:27]
	v_mfma_f32_16x16x32_bf16 v[40:43], v[154:157], v[186:189], v[40:43]
	v_mfma_f32_16x16x32_bf16 v[40:43], v[158:161], v[190:193], v[40:43]
	v_mfma_f32_16x16x32_bf16 v[56:59], v[154:157], v[178:181], v[56:59]
	v_mfma_f32_16x16x32_bf16 v[56:59], v[158:161], v[182:185], v[56:59]
	s_setprio 0
	s_setprio 1
	v_mfma_f32_16x16x32_bf16 v[60:63], v[162:165], v[178:181], v[60:63]
	v_mfma_f32_16x16x32_bf16 v[60:63], v[166:169], v[182:185], v[60:63]
	v_mfma_f32_16x16x32_bf16 v[44:47], v[162:165], v[186:189], v[44:47]
	v_mfma_f32_16x16x32_bf16 v[44:47], v[166:169], v[190:193], v[44:47]
	v_mfma_f32_16x16x32_bf16 v[28:31], v[162:165], v[194:197], v[28:31]
	v_mfma_f32_16x16x32_bf16 v[28:31], v[166:169], v[198:201], v[28:31]
	v_mfma_f32_16x16x32_bf16 v[12:15], v[162:165], v[202:205], v[12:15]
	v_mfma_f32_16x16x32_bf16 v[12:15], v[166:169], v[206:209], v[12:15]
	v_mfma_f32_16x16x32_bf16 v[4:7], v[170:173], v[202:205], v[4:7]
	v_mfma_f32_16x16x32_bf16 v[4:7], v[174:177], v[206:209], v[4:7]
	v_mfma_f32_16x16x32_bf16 v[20:23], v[170:173], v[194:197], v[20:23]
	v_mfma_f32_16x16x32_bf16 v[20:23], v[174:177], v[198:201], v[20:23]
	v_mfma_f32_16x16x32_bf16 v[36:39], v[170:173], v[186:189], v[36:39]
	v_mfma_f32_16x16x32_bf16 v[36:39], v[174:177], v[190:193], v[36:39]
	v_mfma_f32_16x16x32_bf16 v[52:55], v[170:173], v[178:181], v[52:55]
	v_mfma_f32_16x16x32_bf16 v[52:55], v[174:177], v[182:185], v[52:55]
	s_setprio 0
	s_barrier
	ds_read_b128 v[146:149], v220
	ds_read_b128 v[150:153], v220 offset:1024
	ds_read_b128 v[154:157], v220 offset:2048
	ds_read_b128 v[158:161], v220 offset:3072
	ds_read_b128 v[162:165], v221
	ds_read_b128 v[166:169], v221 offset:1024
	ds_read_b128 v[170:173], v221 offset:2048
	ds_read_b128 v[174:177], v221 offset:3072
	s_add_u32 s38, s38, 0x80000
	s_addc_u32 s39, s39, 0
	s_mov_b32 m0, s45
	ds_read_b128 v[178:181], v145 offset:32768
	ds_read_b128 v[182:185], v145 offset:33792
	ds_read_b128 v[186:189], v145 offset:34816
	ds_read_b128 v[190:193], v145 offset:35840
	ds_read_b128 v[194:197], v145 offset:36864
	ds_read_b128 v[198:201], v145 offset:37888
	ds_read_b128 v[202:205], v145 offset:38912
	ds_read_b128 v[206:209], v145 offset:39936
	global_load_lds_dwordx4 v136, s[38:39]
	s_mov_b32 m0, s46
	s_nop 0
	global_load_lds_dwordx4 v134, s[38:39]
	s_waitcnt vmcnt(8)
	s_waitcnt lgkmcnt(0)
	s_barrier
	s_setprio 1
	s_waitcnt lgkmcnt(0)
	v_mfma_f32_16x16x32_bf16 v[128:131], v[146:149], v[178:181], v[128:131]
	v_mfma_f32_16x16x32_bf16 v[128:131], v[150:153], v[182:185], v[128:131]
	v_mfma_f32_16x16x32_bf16 v[112:115], v[146:149], v[186:189], v[112:115]
	v_mfma_f32_16x16x32_bf16 v[112:115], v[150:153], v[190:193], v[112:115]
	v_mfma_f32_16x16x32_bf16 v[96:99], v[146:149], v[194:197], v[96:99]
	v_mfma_f32_16x16x32_bf16 v[96:99], v[150:153], v[198:201], v[96:99]
	v_mfma_f32_16x16x32_bf16 v[80:83], v[146:149], v[202:205], v[80:83]
	v_mfma_f32_16x16x32_bf16 v[80:83], v[150:153], v[206:209], v[80:83]
	v_mfma_f32_16x16x32_bf16 v[72:75], v[154:157], v[202:205], v[72:75]
	v_mfma_f32_16x16x32_bf16 v[72:75], v[158:161], v[206:209], v[72:75]
	v_mfma_f32_16x16x32_bf16 v[88:91], v[154:157], v[194:197], v[88:91]
	v_mfma_f32_16x16x32_bf16 v[88:91], v[158:161], v[198:201], v[88:91]
	v_mfma_f32_16x16x32_bf16 v[104:107], v[154:157], v[186:189], v[104:107]
	v_mfma_f32_16x16x32_bf16 v[104:107], v[158:161], v[190:193], v[104:107]
	v_mfma_f32_16x16x32_bf16 v[120:123], v[154:157], v[178:181], v[120:123]
	v_mfma_f32_16x16x32_bf16 v[120:123], v[158:161], v[182:185], v[120:123]
	s_setprio 0
	s_setprio 1
	v_mfma_f32_16x16x32_bf16 v[124:127], v[162:165], v[178:181], v[124:127]
	v_mfma_f32_16x16x32_bf16 v[124:127], v[166:169], v[182:185], v[124:127]
	v_mfma_f32_16x16x32_bf16 v[108:111], v[162:165], v[186:189], v[108:111]
	v_mfma_f32_16x16x32_bf16 v[108:111], v[166:169], v[190:193], v[108:111]
	v_mfma_f32_16x16x32_bf16 v[92:95], v[162:165], v[194:197], v[92:95]
	v_mfma_f32_16x16x32_bf16 v[92:95], v[166:169], v[198:201], v[92:95]
	v_mfma_f32_16x16x32_bf16 v[76:79], v[162:165], v[202:205], v[76:79]
	v_mfma_f32_16x16x32_bf16 v[76:79], v[166:169], v[206:209], v[76:79]
	v_mfma_f32_16x16x32_bf16 v[68:71], v[170:173], v[202:205], v[68:71]
	v_mfma_f32_16x16x32_bf16 v[68:71], v[174:177], v[206:209], v[68:71]
	v_mfma_f32_16x16x32_bf16 v[84:87], v[170:173], v[194:197], v[84:87]
	v_mfma_f32_16x16x32_bf16 v[84:87], v[174:177], v[198:201], v[84:87]
	v_mfma_f32_16x16x32_bf16 v[100:103], v[170:173], v[186:189], v[100:103]
	v_mfma_f32_16x16x32_bf16 v[100:103], v[174:177], v[190:193], v[100:103]
	v_mfma_f32_16x16x32_bf16 v[116:119], v[170:173], v[178:181], v[116:119]
	v_mfma_f32_16x16x32_bf16 v[116:119], v[174:177], v[182:185], v[116:119]
	s_setprio 0
	s_barrier
	s_mov_b32 m0, s50
	v_lshl_add_u64 v[142:143], v[142:143], 0, s[64:65]
	s_add_u32 s18, s18, 0x80080
	ds_read_b128 v[178:181], v145 offset:49152
	ds_read_b128 v[182:185], v145 offset:50176
	ds_read_b128 v[186:189], v145 offset:51200
	ds_read_b128 v[190:193], v145 offset:52224
	ds_read_b128 v[194:197], v145 offset:53248
	ds_read_b128 v[198:201], v145 offset:54272
	ds_read_b128 v[202:205], v145 offset:55296
	ds_read_b128 v[206:209], v145 offset:56320
	global_load_lds_dwordx4 v[142:143], off
	v_lshl_add_u64 v[142:143], v[210:211], 0, s[64:65]
	s_mov_b32 m0, s51
	s_addc_u32 s19, s19, 0
	global_load_lds_dwordx4 v[142:143], off
	v_lshl_add_u64 v[142:143], s[18:19], 0, v[2:3]
	s_mov_b32 m0, s57
	s_nop 0
	global_load_lds_dwordx4 v[142:143], off
	v_lshl_add_u64 v[142:143], s[18:19], 0, v[132:133]
	s_mov_b32 m0, s58
	s_nop 0
	global_load_lds_dwordx4 v[142:143], off
	v_lshl_add_u64 v[142:143], v[212:213], 0, s[64:65]
	s_mov_b32 m0, s52
	s_nop 0
	global_load_lds_dwordx4 v[142:143], off
	v_lshl_add_u64 v[142:143], v[214:215], 0, s[64:65]
	s_mov_b32 m0, s53
	s_nop 0
	global_load_lds_dwordx4 v[142:143], off
	s_waitcnt vmcnt(8)
	s_waitcnt lgkmcnt(0)
	s_barrier
	s_setprio 1
	s_waitcnt lgkmcnt(0)
	v_mfma_f32_16x16x32_bf16 v[64:67], v[146:149], v[178:181], v[64:67]
	v_mfma_f32_16x16x32_bf16 v[64:67], v[150:153], v[182:185], v[64:67]
	v_mfma_f32_16x16x32_bf16 v[48:51], v[146:149], v[186:189], v[48:51]
	v_mfma_f32_16x16x32_bf16 v[48:51], v[150:153], v[190:193], v[48:51]
	v_mfma_f32_16x16x32_bf16 v[32:35], v[146:149], v[194:197], v[32:35]
	v_mfma_f32_16x16x32_bf16 v[32:35], v[150:153], v[198:201], v[32:35]
	v_mfma_f32_16x16x32_bf16 v[16:19], v[146:149], v[202:205], v[16:19]
	v_mfma_f32_16x16x32_bf16 v[16:19], v[150:153], v[206:209], v[16:19]
	v_mfma_f32_16x16x32_bf16 v[8:11], v[154:157], v[202:205], v[8:11]
	v_mfma_f32_16x16x32_bf16 v[8:11], v[158:161], v[206:209], v[8:11]
	v_mfma_f32_16x16x32_bf16 v[24:27], v[154:157], v[194:197], v[24:27]
	v_mfma_f32_16x16x32_bf16 v[24:27], v[158:161], v[198:201], v[24:27]
	v_mfma_f32_16x16x32_bf16 v[40:43], v[154:157], v[186:189], v[40:43]
	v_mfma_f32_16x16x32_bf16 v[40:43], v[158:161], v[190:193], v[40:43]
	v_mfma_f32_16x16x32_bf16 v[56:59], v[154:157], v[178:181], v[56:59]
	v_mfma_f32_16x16x32_bf16 v[56:59], v[158:161], v[182:185], v[56:59]
	s_setprio 0
	s_setprio 1
	v_mfma_f32_16x16x32_bf16 v[60:63], v[162:165], v[178:181], v[60:63]
	v_mfma_f32_16x16x32_bf16 v[60:63], v[166:169], v[182:185], v[60:63]
	v_mfma_f32_16x16x32_bf16 v[44:47], v[162:165], v[186:189], v[44:47]
	v_mfma_f32_16x16x32_bf16 v[44:47], v[166:169], v[190:193], v[44:47]
	v_mfma_f32_16x16x32_bf16 v[28:31], v[162:165], v[194:197], v[28:31]
	v_mfma_f32_16x16x32_bf16 v[28:31], v[166:169], v[198:201], v[28:31]
	v_mfma_f32_16x16x32_bf16 v[12:15], v[162:165], v[202:205], v[12:15]
	v_mfma_f32_16x16x32_bf16 v[12:15], v[166:169], v[206:209], v[12:15]
	s_add_i32 s74, s74, 2
	v_mfma_f32_16x16x32_bf16 v[4:7], v[170:173], v[202:205], v[4:7]
	v_mfma_f32_16x16x32_bf16 v[4:7], v[174:177], v[206:209], v[4:7]
	s_add_u32 s34, s34, 0x100
	s_addc_u32 s35, s35, 0
	v_mfma_f32_16x16x32_bf16 v[20:23], v[170:173], v[194:197], v[20:23]
	v_mfma_f32_16x16x32_bf16 v[20:23], v[174:177], v[198:201], v[20:23]
	s_add_u32 s71, s71, 0x100
	s_addc_u32 s73, s73, 0
	s_cmp_gt_u32 s74, 29
	s_cbranch_scc1 .Lgu_keep
	s_add_u32 s18, s34, 0xfff80080
	s_addc_u32 s19, s35, -1
	s_cmp_eq_u32 s74, 28
	s_cselect_b32 s39, s13, s19
	s_cselect_b32 s38, s69, s18
	s_cselect_b32 s19, s11, s73
	s_cselect_b32 s18, s70, s71
.Lgu_keep:
	v_mfma_f32_16x16x32_bf16 v[36:39], v[170:173], v[186:189], v[36:39]
	v_mfma_f32_16x16x32_bf16 v[36:39], v[174:177], v[190:193], v[36:39]
	s_cmp_gt_u32 s74, 29
	v_mfma_f32_16x16x32_bf16 v[52:55], v[170:173], v[178:181], v[52:55]
	v_mfma_f32_16x16x32_bf16 v[52:55], v[174:177], v[182:185], v[52:55]
	s_setprio 0
	s_barrier
	s_cbranch_scc0 .LBB0_3116
	s_and_b64 vcc, exec, s[8:9]
	s_cbranch_vccz .LBB0_3119
	s_barrier
